# GLA kdec gate pre-activation on f32 matrix cores (v_mfma_f32_16x16x4_f32) + per-lane 16-token scan, decayed keys rewritten 4 columns per LDS access
# speedup vs baseline: 1.0032x; 1.0032x over previous
; __device__ __forceinline__ void phase_gla_kdec(Frame& F) {
;     ...
;     for (int unit = F.bid; unit < NB * (SEQ / CH); unit += F.G) {
.LBB0_813:
	s_and_b32 s0, s92, 0x80
	s_mov_b32 s1, 0
	v_cndmask_b32_e64 v0, 0, 1, s[72:73]
	s_cmp_eq_u64 s[0:1], 0
	v_cmp_ne_u32_e64 s[8:9], 1, v0
	s_barrier
	s_cbranch_scc1 .LBB0_822
	s_and_b64 vcc, exec, s[8:9]
	s_cbranch_vccnz .LBB0_821
; __device__ __forceinline__ void phase_gla_kdec(Frame& F) {
;     ...
;     const int j = F.tid, lane = F.lane, w = F.wave, g = lane >> 4, li = lane & 15, q4 = li >> 2, p4 = li & 3;
;     float w2c[RANK];
; #pragma unroll
;     for (int r = 0; r < RANK; ++r) w2c[r] = w2[r * QKW + j];
;     const float bgc = bg[j];
;     for (int unit = F.bid; unit < NB * (SEQ / CH); unit += F.G) {
;         const size_t m0 = (size_t)unit * CH;
	v_mbcnt_lo_u32_b32 v0, -1, 0
	v_mbcnt_hi_u32_b32 v12, -1, v0
	s_and_b32 s0, s90, 0xffffffc0
	v_add_u32_e32 v0, s0, v12
	v_ashrrev_i32_e32 v1, 31, v0
	v_readlane_b32 s36, v252, 18
	v_lshlrev_b64 v[2:3], 2, v[0:1]
	v_readlane_b32 s37, v252, 19
	v_readlane_b32 s38, v252, 20
	v_readlane_b32 s39, v252, 21
	v_lshl_add_u64 v[4:5], s[36:37], 0, v[2:3]
	v_add_co_u32_e32 v6, vcc, 0x1000, v4
	s_add_u32 s10, s34, 0x4000000
	s_nop 0
	v_addc_co_u32_e32 v7, vcc, 0, v5, vcc
	v_add_co_u32_e32 v8, vcc, 0x2000, v4
	s_addc_u32 s11, s35, 0
	s_nop 0
	v_addc_co_u32_e32 v9, vcc, 0, v5, vcc
	v_add_co_u32_e32 v10, vcc, 0x3000, v4
	s_mov_b64 s[0:1], 0x300000
	s_nop 0
	v_addc_co_u32_e32 v11, vcc, 0, v5, vcc
	v_and_b32_e32 v232, 15, v12
	v_lshrrev_b32_e32 v233, 4, v12
	v_lshlrev_b32_e32 v232, 4, v232
	v_mov_b32_e32 v234, s90
	v_and_b32_e32 v234, 0xffffffc0, v234
	v_lshl_add_u32 v232, v234, 2, v232
	v_lshl_add_u32 v234, v233, 13, v232
	v_add_u32_e32 v235, 0x1000, v234
	global_load_dwordx4 v[16:19], v234, s[36:37]
	global_load_dwordx4 v[20:23], v234, s[36:37] offset:2048
	global_load_dwordx4 v[24:27], v235, s[36:37]
	global_load_dwordx4 v[224:227], v235, s[36:37] offset:2048
	global_load_dwordx4 v[228:231], v232, s[38:39]
	v_add_co_u32_e32 v6, vcc, 0x4000, v4
	s_mov_b32 s13, 0
	s_nop 0
	v_addc_co_u32_e32 v7, vcc, 0, v5, vcc
	v_add_co_u32_e32 v8, vcc, 0x5000, v4
	v_and_b32_e32 v30, 15, v12
	s_nop 0
	v_addc_co_u32_e32 v9, vcc, 0, v5, vcc
	v_add_co_u32_e32 v10, vcc, 0x6000, v4
	v_lshrrev_b32_e32 v1, 4, v12
	s_nop 0
	v_addc_co_u32_e32 v11, vcc, 0, v5, vcc
	v_add_co_u32_e32 v4, vcc, 0x7000, v4
	v_lshlrev_b32_e32 v32, 11, v30
	s_nop 0
	v_addc_co_u32_e32 v5, vcc, 0, v5, vcc
	v_lshl_add_u64 v[4:5], s[38:39], 0, v[2:3]
	v_lshl_add_u64 v[2:3], s[34:35], 0, v[2:3]
	v_lshl_add_u64 v[28:29], v[2:3], 0, s[0:1]
	s_add_u32 s0, s34, 0xe000000
	s_addc_u32 s1, s35, 0
	s_lshl_b32 s12, s3, 1
	s_add_i32 s6, 0, 0x19800
	s_lshl_b64 s[4:5], s[12:13], 12
	v_lshlrev_b32_e32 v4, 3, v1
	v_mov_b32_e32 v33, 0
	s_add_u32 s4, s34, s4
	v_bfe_u32 v6, v12, 2, 2
	v_lshl_or_b32 v7, s3, 7, v4
	v_lshl_add_u64 v[2:3], s[34:35], 0, v[32:33]
	s_addc_u32 s5, s35, s5
	v_lshlrev_b32_e32 v32, 4, v12
	v_or_b32_e32 v9, v4, v6
	v_lshl_add_u64 v[4:5], s[4:5], 0, v[32:33]
	s_mov_b64 s[4:5], 0xa000000
	v_lshlrev_b32_e32 v32, 1, v7
	v_lshl_add_u64 v[34:35], v[4:5], 0, s[4:5]
	v_lshl_add_u64 v[2:3], v[2:3], 0, v[32:33]
	s_mov_b64 s[4:5], 0x2c0000
	v_lshl_add_u64 v[36:37], v[2:3], 0, s[4:5]
	v_add_u32_e32 v2, 64, v32
	v_mov_b32_e32 v3, v33
	v_lshl_add_u64 v[46:47], s[0:1], 0, v[2:3]
	v_add_u32_e32 v2, 0x60, v7
	v_lshl_add_u64 v[38:39], s[0:1], 0, v[32:33]
	v_or_b32_e32 v32, 0x80, v32
	v_ashrrev_i32_e32 v3, 31, v2
	v_lshlrev_b32_e32 v8, 2, v30
	v_lshl_add_u64 v[48:49], s[0:1], 0, v[32:33]
	v_lshl_add_u64 v[50:51], v[2:3], 1, s[0:1]
	v_lshlrev_b32_e32 v2, 8, v1
	s_add_i32 s0, 0, 0x11400
	v_lshlrev_b32_e32 v10, 3, v12
	v_add3_u32 v4, s6, v8, v2
	s_movk_i32 s1, 0x210
	v_mov_b32_e32 v2, s0
	v_mad_u32_u24 v2, v9, s1, v2
	v_and_b32_e32 v3, 24, v10
	s_lshl_b32 s4, s3, 6
	v_add3_u32 v99, v2, v3, s4
	v_ashrrev_i32_e32 v52, 6, v0
	s_movk_i32 s4, 0x410
	v_lshlrev_b32_e32 v7, 4, v0
	v_mul_lo_u32 v5, v52, s4
	v_and_b32_e32 v32, 0x3f0, v7
	v_add3_u32 v101, 0, v5, v32
	v_add_u32_e32 v5, 0x200, v0
	v_ashrrev_i32_e32 v54, 6, v5
	v_mul_lo_u32 v8, v54, s4
	v_add3_u32 v102, 0, v8, v32
	v_add_u32_e32 v8, 0x400, v0
	v_ashrrev_i32_e32 v56, 6, v8
	v_mul_lo_u32 v9, v56, s4
	v_add3_u32 v103, 0, v9, v32
	v_add_u32_e32 v9, 0x600, v0
	v_ashrrev_i32_e32 v58, 6, v9
	v_lshlrev_b32_e32 v2, 3, v0
	v_mul_lo_u32 v11, v58, s4
	v_add3_u32 v104, 0, v11, v32
	v_add_u32_e32 v11, 0x800, v0
	v_ashrrev_i32_e32 v68, 5, v0
	v_ashrrev_i32_e32 v70, 5, v5
	v_and_b32_e32 v2, 0xffffffc0, v2
	v_and_b32_e32 v5, 56, v10
	v_ashrrev_i32_e32 v60, 6, v11
	v_add3_u32 v109, s6, v2, v5
	v_add3_u32 v110, 0, v2, v5
	v_mul_lo_u32 v2, v68, s1
	v_mul_lo_u32 v11, v60, s4
	v_add_u32_e32 v2, s0, v2
	v_and_b32_e32 v5, 0x1c0, v7
	v_add3_u32 v105, 0, v11, v32
	v_add_u32_e32 v11, 0xa00, v0
	v_add3_u32 v111, v2, v5, v3
	v_mul_lo_u32 v2, v70, s1
	v_ashrrev_i32_e32 v62, 6, v11
	v_ashrrev_i32_e32 v72, 5, v8
	v_add_u32_e32 v2, s0, v2
	v_mul_lo_u32 v11, v62, s4
	v_add3_u32 v112, v2, v5, v3
	v_mul_lo_u32 v2, v72, s1
	v_add3_u32 v106, 0, v11, v32
	v_add_u32_e32 v11, 0xc00, v0
	v_ashrrev_i32_e32 v74, 5, v9
	v_add_u32_e32 v2, s0, v2
	v_ashrrev_i32_e32 v64, 6, v11
	v_add3_u32 v113, v2, v5, v3
	v_mul_lo_u32 v2, v74, s1
	v_mul_lo_u32 v11, v64, s4
	v_add_u32_e32 v2, s0, v2
	v_add3_u32 v107, 0, v11, v32
	v_add_u32_e32 v11, 0xe00, v0
	v_add3_u32 v114, v2, v5, v3
	v_mul_u32_u24_e32 v2, 0x410, v6
	s_movk_i32 s0, 0x2080
	s_lshl_b32 s7, s3, 12
	v_ashrrev_i32_e32 v66, 6, v11
	s_lshl_b32 s19, s2, 2
	s_lshl_b32 s20, s33, 2
	v_mad_u32_u24 v1, v1, s0, v2
	s_mul_i32 s0, s2, 0x60000
	v_mul_lo_u32 v11, v66, s4
	v_and_b32_e32 v2, 3, v12
	s_mul_hi_i32 s1, s2, 0x60000
	s_add_u32 s0, s34, s0
	v_lshl_add_u32 v97, v0, 1, 0
	v_add3_u32 v108, 0, v11, v32
	v_lshl_add_u64 v[76:77], s[10:11], 0, v[32:33]
	v_and_b32_e32 v32, 0x1f0, v7
	v_lshlrev_b32_e32 v2, 3, v2
	v_and_b32_e32 v0, 31, v0
	s_addc_u32 s1, s35, s1
	v_lshl_add_u64 v[78:79], s[10:11], 0, v[32:33]
	v_add3_u32 v115, v1, v2, 0
	v_lshlrev_b32_e32 v32, 4, v0
	s_movk_i32 s21, 0x1800
	v_mov_b64_e32 v[0:1], s[0:1]
	v_mad_i64_i32 v[2:3], s[0:1], v74, s21, v[0:1]
	s_mov_b64 s[0:1], 0x4000a00
	s_nop 0
	v_lshl_add_u64 v[80:81], v[2:3], 0, s[0:1]
	v_mad_i64_i32 v[2:3], s[4:5], v72, s21, v[0:1]
	v_lshl_add_u64 v[82:83], v[2:3], 0, s[0:1]
	v_mad_i64_i32 v[2:3], s[4:5], v70, s21, v[0:1]
	v_mad_i64_i32 v[0:1], s[4:5], v68, s21, v[0:1]
	s_movk_i32 s18, 0x1000
	v_add_u32_e32 v98, 0x1000, v97
	v_or_b32_e32 v40, 16, v30
	v_or_b32_e32 v42, 32, v30
	v_or_b32_e32 v44, 48, v30
	v_add_u32_e32 v100, 0x4200, v99
	v_ashrrev_i32_e32 v53, 31, v52
	v_ashrrev_i32_e32 v55, 31, v54
	v_ashrrev_i32_e32 v57, 31, v56
	v_ashrrev_i32_e32 v59, 31, v58
	v_ashrrev_i32_e32 v61, 31, v60
	v_ashrrev_i32_e32 v63, 31, v62
	v_ashrrev_i32_e32 v65, 31, v64
	v_ashrrev_i32_e32 v67, 31, v66
	v_ashrrev_i32_e32 v69, 31, v68
	v_ashrrev_i32_e32 v71, 31, v70
	v_ashrrev_i32_e32 v73, 31, v72
	v_ashrrev_i32_e32 v75, 31, v74
	s_mul_hi_i32 s11, s33, 0x60000
	s_mul_i32 s10, s33, 0x60000
	v_lshl_add_u64 v[84:85], v[2:3], 0, s[0:1]
	v_lshl_add_u64 v[86:87], v[0:1], 0, s[0:1]
	v_add_u32_e32 v116, s7, v4
	s_mov_b32 s22, 0xbfb8aa3b
	s_mov_b32 s23, 0x3d800000
	s_movk_i32 s24, 0x7fff
	s_mov_b64 s[12:13], 0x200
	s_mov_b32 s14, s2
	v_readlane_b32 s40, v252, 22
	v_readlane_b32 s41, v252, 23
	v_readlane_b32 s42, v252, 24
	v_readlane_b32 s43, v252, 25
	v_readlane_b32 s44, v252, 26
	v_readlane_b32 s45, v252, 27
	v_readlane_b32 s46, v252, 28
	v_readlane_b32 s47, v252, 29
	v_readlane_b32 s48, v252, 30
	v_readlane_b32 s49, v252, 31
	v_readlane_b32 s50, v252, 32
	v_readlane_b32 s51, v252, 33
	s_branch .LBB0_817

; #define LAS __attribute__((address_space(3)))
; #define GAS __attribute__((address_space(1)))
; __device__ __forceinline__ void phase_gla_kdec(Frame& F) {
;     ...
;     for (int unit = F.bid; unit < NB * (SEQ / CH); unit += F.G) {
;         const size_t m0 = (size_t)unit * CH;
;         __syncthreads();
;         {
;             f32x4 ga[4];
; #pragma unroll
;             for (int mb = 0; mb < 4; ++mb) ga[mb] = (f32x4){0.f, 0.f, 0.f, 0.f};
; #pragma unroll
;             for (int ks = 0; ks < 4; ++ks) { const int k0 = 128 * w + 32 * ks + 8 * g; const bf16x8 bfr = *(const GAS bf16x8*)(WGT + li * D + k0);
; #pragma unroll
;                 for (int mb = 0; mb < 4; ++mb) { const bf16x8 afr = *(const GAS bf16x8*)(H2 + (m0 + 16 * mb + li) * D + k0); ga[mb] = __builtin_amdgcn_mfma_f32_16x16x32_bf16(afr, bfr, ga[mb], 0, 0, 0); } }
; #pragma unroll
;             for (int mb = 0; mb < 4; ++mb)
; #pragma unroll
;                 for (int i = 0; i < 4; ++i) gpart[(w * 64 + 16 * mb + 4 * g + i) * 16 + li] = ga[mb][i];
;         }
; #pragma unroll
;         for (int i = 0; i < 8; ++i) { const int idx = F.tid + NTHR * i, row = idx >> 6, ch = idx & 63;
;             *(LAS u32x4*)(kt + row * KP + ch * 8) = *(const GAS u32x4*)(QKVR + (m0 + row) * NQKVR + QKW + ch * 8); }
;         u32x4 rv[4];
; #pragma unroll
;         for (int i = 0; i < 4; ++i) { const int idx = F.tid + NTHR * i, row = idx >> 5, ch = idx & 31; rv[i] = *(const GAS u32x4*)(QKVR + (m0 + row) * NQKVR + 2 * QKW + ch * 8); }
;         __syncthreads();
.LBB0_817:
	s_ashr_i32 s15, s14, 31
	s_lshl_b64 s[16:17], s[14:15], 6
	s_waitcnt vmcnt(11)
	v_mov_b32_e32 v1, s17
	v_or_b32_e32 v0, s16, v30
	s_waitcnt vmcnt(9)
	v_mov_b32_e32 v9, s17
	v_or_b32_e32 v8, s16, v40
	s_waitcnt vmcnt(8)
	v_mov_b32_e32 v13, s17
	v_or_b32_e32 v12, s16, v42
	v_mov_b32_e32 v89, s17
	v_or_b32_e32 v88, s16, v44
	v_lshlrev_b64 v[154:155], 11, v[0:1]
	v_lshlrev_b64 v[162:163], 11, v[8:9]
	v_lshlrev_b64 v[166:167], 11, v[12:13]
	v_lshlrev_b64 v[168:169], 11, v[88:89]
	v_lshl_add_u64 v[4:5], v[38:39], 0, v[154:155]
	v_lshl_add_u64 v[8:9], v[38:39], 0, v[162:163]
	v_lshl_add_u64 v[12:13], v[38:39], 0, v[166:167]
	v_lshl_add_u64 v[88:89], v[38:39], 0, v[168:169]
	s_barrier
	global_load_dwordx4 v[0:3], v[36:37], off
	v_lshl_add_u64 v[92:93], v[46:47], 0, v[154:155]
	global_load_dwordx4 v[4:7], v[4:5], off
	v_lshl_add_u64 v[122:123], v[46:47], 0, v[162:163]
	global_load_dwordx4 v[8:11], v[8:9], off
	v_lshl_add_u64 v[126:127], v[46:47], 0, v[166:167]
	global_load_dwordx4 v[12:15], v[12:13], off
	v_lshl_add_u64 v[130:131], v[46:47], 0, v[168:169]
	global_load_dwordx4 v[88:91], v[88:89], off
	s_nop 0
	global_load_dwordx4 v[92:95], v[92:93], off
	s_nop 0
	global_load_dwordx4 v[118:121], v[36:37], off offset:64
	v_lshl_add_u64 v[134:135], v[48:49], 0, v[154:155]
	global_load_dwordx4 v[122:125], v[122:123], off
	v_lshl_add_u64 v[142:143], v[48:49], 0, v[162:163]
	global_load_dwordx4 v[126:129], v[126:127], off
	v_lshl_add_u64 v[146:147], v[48:49], 0, v[166:167]
	global_load_dwordx4 v[130:133], v[130:131], off
	s_nop 0
	global_load_dwordx4 v[134:137], v[134:135], off
	s_nop 0
	global_load_dwordx4 v[138:141], v[36:37], off offset:128
	v_lshl_add_u64 v[150:151], v[48:49], 0, v[168:169]
	global_load_dwordx4 v[142:145], v[142:143], off
	v_lshl_add_u64 v[154:155], v[50:51], 0, v[154:155]
	global_load_dwordx4 v[146:149], v[146:147], off
	v_lshl_add_u64 v[166:167], v[50:51], 0, v[166:167]
	global_load_dwordx4 v[150:153], v[150:151], off
	s_nop 0
	global_load_dwordx4 v[154:157], v[154:155], off
	s_nop 0
	global_load_dwordx4 v[158:161], v[36:37], off offset:192
	v_lshl_add_u64 v[162:163], v[50:51], 0, v[162:163]
	global_load_dwordx4 v[162:165], v[162:163], off
	v_lshl_add_u64 v[170:171], s[16:17], 0, v[54:55]
	v_lshl_add_u64 v[172:173], s[16:17], 0, v[56:57]
	v_lshl_add_u64 v[174:175], s[16:17], 0, v[58:59]
	v_lshl_add_u64 v[176:177], s[16:17], 0, v[64:65]
	s_waitcnt vmcnt(16)
	v_mfma_f32_16x16x32_bf16 v[4:7], v[4:7], v[0:3], 0
	s_waitcnt vmcnt(15)
	v_mfma_f32_16x16x32_bf16 v[8:11], v[8:11], v[0:3], 0
	s_waitcnt vmcnt(14)
	v_mfma_f32_16x16x32_bf16 v[12:15], v[12:15], v[0:3], 0
	s_waitcnt vmcnt(13)
	v_mfma_f32_16x16x32_bf16 v[0:3], v[88:91], v[0:3], 0
	global_load_dwordx4 v[88:91], v[166:167], off
	v_lshl_add_u64 v[166:167], s[16:17], 0, v[52:53]
	s_waitcnt vmcnt(10)
	v_mfma_f32_16x16x32_bf16 v[12:15], v[126:129], v[118:121], v[12:15]
	v_mad_u64_u32 v[126:127], s[0:1], v166, s21, v[76:77]
	v_mad_u64_u32 v[128:129], s[0:1], v170, s21, v[76:77]
	v_mfma_f32_16x16x32_bf16 v[4:7], v[92:95], v[118:121], v[4:7]
	v_lshl_add_u64 v[92:93], v[50:51], 0, v[168:169]
	global_load_dwordx4 v[92:95], v[92:93], off
	v_mad_i32_i24 v127, v167, s21, v127
	s_waitcnt vmcnt(6)
	v_mfma_f32_16x16x32_bf16 v[12:15], v[146:149], v[138:141], v[12:15]
	v_mad_i32_i24 v129, v171, s21, v129
	v_mfma_f32_16x16x32_bf16 v[8:11], v[122:125], v[118:121], v[8:11]
	v_lshl_add_u64 v[122:123], s[16:17], 0, v[60:61]
	v_lshl_add_u64 v[124:125], s[16:17], 0, v[62:63]
	v_mad_u64_u32 v[178:179], s[0:1], v124, s21, v[76:77]
	v_mfma_f32_16x16x32_bf16 v[0:3], v[130:133], v[118:121], v[0:3]
	v_mad_u64_u32 v[130:131], s[0:1], v172, s21, v[76:77]
	v_mad_u64_u32 v[132:133], s[0:1], v174, s21, v[76:77]
	v_mfma_f32_16x16x32_bf16 v[4:7], v[134:137], v[138:141], v[4:7]
	v_mad_u64_u32 v[134:135], s[0:1], v122, s21, v[76:77]
	v_mad_i32_i24 v131, v173, s21, v131
	v_mfma_f32_16x16x32_bf16 v[8:11], v[142:145], v[138:141], v[8:11]
	v_mad_u64_u32 v[142:143], s[0:1], v176, s21, v[76:77]
	v_mad_i32_i24 v133, v175, s21, v133
	v_mad_i32_i24 v135, v123, s21, v135
	v_mad_i32_i24 v143, v177, s21, v143
	s_waitcnt vmcnt(5)
	v_mfma_f32_16x16x32_bf16 v[0:3], v[150:153], v[138:141], v[0:3]
	v_mad_i32_i24 v179, v125, s21, v179
	global_load_dwordx4 v[118:121], v[126:127], off offset:1024
	global_load_dwordx4 v[122:125], v[128:129], off offset:1024
	s_nop 0
	global_load_dwordx4 v[126:129], v[130:131], off offset:1024
	s_nop 0
	global_load_dwordx4 v[130:133], v[132:133], off offset:1024
	s_nop 0
	global_load_dwordx4 v[134:137], v[134:135], off offset:1024
	s_nop 0
	global_load_dwordx4 v[138:141], v[178:179], off offset:1024
	s_waitcnt vmcnt(9)
	v_mfma_f32_16x16x32_bf16 v[4:7], v[154:157], v[158:161], v[4:7]
	s_waitcnt vmcnt(8)
	v_mfma_f32_16x16x32_bf16 v[8:11], v[162:165], v[158:161], v[8:11]
	s_waitcnt vmcnt(7)
	v_mfma_f32_16x16x32_bf16 v[12:15], v[88:91], v[158:161], v[12:15]
	v_lshl_add_u64 v[88:89], s[16:17], 0, v[66:67]
	v_mad_u64_u32 v[144:145], s[0:1], v88, s21, v[76:77]
	v_mad_i32_i24 v145, v89, s21, v145
	global_load_dwordx4 v[88:91], v[142:143], off offset:1024
	s_nop 0
	global_load_dwordx4 v[142:145], v[144:145], off offset:1024
	s_waitcnt vmcnt(8)
	v_mfma_f32_16x16x32_bf16 v[0:3], v[92:95], v[158:161], v[0:3]
	ds_write2_b32 v116, v4, v5 offset1:16
	ds_write2_b32 v116, v6, v7 offset0:32 offset1:48
	v_add_u32_e32 v4, 0x400, v116
	ds_write2_b32 v4, v8, v9 offset1:16
	ds_write2_b32 v4, v10, v11 offset0:32 offset1:48
	v_add_u32_e32 v4, 0x800, v116
	ds_write2_b32 v4, v12, v13 offset1:16
	ds_write2_b32 v4, v14, v15 offset0:32 offset1:48
	v_add_u32_e32 v4, 0xc00, v116
	v_lshl_add_u64 v[8:9], s[16:17], 0, v[72:73]
	ds_write2_b32 v4, v0, v1 offset1:16
	ds_write2_b32 v4, v2, v3 offset0:32 offset1:48
	s_waitcnt vmcnt(7)
	ds_write_b128 v101, v[118:121] offset:4096
	s_waitcnt vmcnt(6)
	ds_write_b128 v102, v[122:125] offset:4096
	s_waitcnt vmcnt(5)
	ds_write_b128 v103, v[126:129] offset:4096
	s_waitcnt vmcnt(4)
	ds_write_b128 v104, v[130:133] offset:4096
	s_waitcnt vmcnt(3)
	ds_write_b128 v105, v[134:137] offset:4096
	s_waitcnt vmcnt(2)
	ds_write_b128 v106, v[138:141] offset:4096
	s_waitcnt vmcnt(1)
	ds_write_b128 v107, v[88:91] offset:4096
	s_waitcnt vmcnt(0)
	ds_write_b128 v108, v[142:145] offset:4096
	v_lshl_add_u64 v[0:1], s[16:17], 0, v[68:69]
	v_mad_u64_u32 v[2:3], s[0:1], v0, s21, v[78:79]
	v_mad_u64_u32 v[88:89], s[0:1], v8, s21, v[78:79]
	v_mad_i32_i24 v3, v1, s21, v3
	v_lshl_add_u64 v[0:1], s[16:17], 0, v[70:71]
	v_mad_i32_i24 v89, v9, s21, v89
	v_lshl_add_u64 v[8:9], s[16:17], 0, v[74:75]
	v_mad_u64_u32 v[4:5], s[0:1], v0, s21, v[78:79]
	v_mad_u64_u32 v[90:91], s[0:1], v8, s21, v[78:79]
	v_mad_i32_i24 v5, v1, s21, v5
	v_mad_i32_i24 v91, v9, s21, v91
	global_load_dwordx4 v[0:3], v[2:3], off offset:2048
	s_nop 0
	global_load_dwordx4 v[4:7], v[4:5], off offset:2048
	s_nop 0
	global_load_dwordx4 v[8:11], v[88:89], off offset:2048
	global_load_dwordx4 v[12:15], v[90:91], off offset:2048
	s_waitcnt lgkmcnt(0)
	s_barrier
; #define LAS __attribute__((address_space(3)))
; __device__ __forceinline__ void phase_gla_kdec(Frame& F) {
;     ...
;         { const int sIdx = F.tid >> 3, r2 = (F.tid & 7) * 2; float s0 = 0.f, s1 = 0.f;
; #pragma unroll
;             for (int v = 0; v < 8; ++v) { s0 += gpart[(v * 64 + sIdx) * 16 + r2]; s1 += gpart[(v * 64 + sIdx) * 16 + r2 + 1]; }
;             glr[sIdx * 16 + r2] = s0; glr[sIdx * 16 + r2 + 1] = s1; }
;         __syncthreads();
;         { float gc[CH]; float run = 0.f;
; #pragma unroll
;             for (int s = 0; s < CH; ++s) { float a = bgc;
; #pragma unroll
;                 for (int r4 = 0; r4 < 4; ++r4) { const f32x4 gv = *(const LAS f32x4*)(glr + s * 16 + r4 * 4); a += (gv.x * w2c[4 * r4] + gv.y * w2c[4 * r4 + 1]) + (gv.z * w2c[4 * r4 + 2] + gv.w * w2c[4 * r4 + 3]); }
;                 run += fast_logsigmoid(a) * (1.f / 16.f); gc[s] = run; }
	ds_read2st64_b64 v[88:91], v109 offset1:8
	ds_read2st64_b64 v[92:95], v109 offset0:16 offset1:24
	ds_read2st64_b64 v[118:121], v109 offset0:32 offset1:40
	s_lshl_b64 s[0:1], s[14:15], 11
	s_mov_b32 s16, s19
	s_waitcnt lgkmcnt(2)
	v_pk_add_f32 v[88:89], v[88:89], 0 op_sel_hi:[1,0]
	s_nop 0
	v_pk_add_f32 v[122:123], v[88:89], v[90:91]
	ds_read2st64_b64 v[88:91], v109 offset0:48 offset1:56
	s_waitcnt lgkmcnt(2)
	v_pk_add_f32 v[92:93], v[122:123], v[92:93]
	s_nop 0
	v_pk_add_f32 v[92:93], v[92:93], v[94:95]
	s_waitcnt lgkmcnt(1)
	v_pk_add_f32 v[92:93], v[92:93], v[118:119]
	s_nop 0
	v_pk_add_f32 v[92:93], v[92:93], v[120:121]
	s_waitcnt lgkmcnt(0)
	v_pk_add_f32 v[88:89], v[92:93], v[88:89]
	s_nop 0
	v_pk_add_f32 v[88:89], v[88:89], v[90:91]
	ds_write_b64 v110, v[88:89]
	s_waitcnt lgkmcnt(0)
	s_barrier
	v_mbcnt_lo_u32_b32 v117, -1, 0
	v_mbcnt_hi_u32_b32 v117, -1, v117
	v_and_b32_e32 v118, 15, v117
	v_lshrrev_b32_e32 v119, 4, v117
	v_lshrrev_b32_e32 v184, 2, v118
	v_and_b32_e32 v186, 3, v118
	v_lshlrev_b32_e32 v184, 10, v184
	v_lshl_or_b32 v184, v186, 6, v184
	v_lshl_or_b32 v184, v119, 4, v184
	ds_read_b128 v[232:235], v184 offset:0
	ds_read_b128 v[236:239], v184 offset:256
	ds_read_b128 v[240:243], v184 offset:512
	ds_read_b128 v[244:247], v184 offset:768
	v_mov_b32_e32 v188, s90
	v_and_b32_e32 v188, 0xffffffc0, v188
	v_lshlrev_b32_e32 v185, 1, v188
	v_lshl_add_u32 v185, v118, 3, v185
	v_mul_u32_u24_e32 v186, 0x4100, v119
	v_add_u32_e32 v185, v185, v186
	v_add_u32_e32 v185, 0x1000, v185
	v_add_u32_e32 v187, v188, v118
	v_lshlrev_b32_e32 v187, 4, v187
	v_add_u32_e32 v187, 0x19800, v187
	v_add_u32_e32 v186, v188, v117
	v_lshlrev_b32_e32 v186, 4, v186
	v_add_u32_e32 v186, 0x19800, v186
	s_waitcnt lgkmcnt(0)
	v_mfma_f32_16x16x4_f32 v[120:123], v232, v16, 0
	v_mfma_f32_16x16x4_f32 v[124:127], v232, v17, 0
	v_mfma_f32_16x16x4_f32 v[128:131], v232, v18, 0
	v_mfma_f32_16x16x4_f32 v[132:135], v232, v19, 0
	v_mfma_f32_16x16x4_f32 v[120:123], v233, v20, v[120:123]
	v_mfma_f32_16x16x4_f32 v[124:127], v233, v21, v[124:127]
	v_mfma_f32_16x16x4_f32 v[128:131], v233, v22, v[128:131]
	v_mfma_f32_16x16x4_f32 v[132:135], v233, v23, v[132:135]
	v_mfma_f32_16x16x4_f32 v[120:123], v234, v24, v[120:123]
	v_mfma_f32_16x16x4_f32 v[124:127], v234, v25, v[124:127]
	v_mfma_f32_16x16x4_f32 v[128:131], v234, v26, v[128:131]
	v_mfma_f32_16x16x4_f32 v[132:135], v234, v27, v[132:135]
	v_mfma_f32_16x16x4_f32 v[120:123], v235, v224, v[120:123]
	v_mfma_f32_16x16x4_f32 v[124:127], v235, v225, v[124:127]
	v_mfma_f32_16x16x4_f32 v[128:131], v235, v226, v[128:131]
	v_mfma_f32_16x16x4_f32 v[132:135], v235, v227, v[132:135]
	v_mfma_f32_16x16x4_f32 v[136:139], v236, v16, 0
	v_mfma_f32_16x16x4_f32 v[140:143], v236, v17, 0
	v_mfma_f32_16x16x4_f32 v[144:147], v236, v18, 0
	v_mfma_f32_16x16x4_f32 v[148:151], v236, v19, 0
	v_mfma_f32_16x16x4_f32 v[136:139], v237, v20, v[136:139]
	v_mfma_f32_16x16x4_f32 v[140:143], v237, v21, v[140:143]
	v_mfma_f32_16x16x4_f32 v[144:147], v237, v22, v[144:147]
	v_mfma_f32_16x16x4_f32 v[148:151], v237, v23, v[148:151]
	v_mfma_f32_16x16x4_f32 v[136:139], v238, v24, v[136:139]
	v_mfma_f32_16x16x4_f32 v[140:143], v238, v25, v[140:143]
	v_mfma_f32_16x16x4_f32 v[144:147], v238, v26, v[144:147]
	v_mfma_f32_16x16x4_f32 v[148:151], v238, v27, v[148:151]
	v_mfma_f32_16x16x4_f32 v[136:139], v239, v224, v[136:139]
	v_mfma_f32_16x16x4_f32 v[140:143], v239, v225, v[140:143]
	v_mfma_f32_16x16x4_f32 v[144:147], v239, v226, v[144:147]
	v_mfma_f32_16x16x4_f32 v[148:151], v239, v227, v[148:151]
	v_mfma_f32_16x16x4_f32 v[152:155], v240, v16, 0
	v_mfma_f32_16x16x4_f32 v[156:159], v240, v17, 0
	v_mfma_f32_16x16x4_f32 v[160:163], v240, v18, 0
	v_mfma_f32_16x16x4_f32 v[164:167], v240, v19, 0
	v_mfma_f32_16x16x4_f32 v[152:155], v241, v20, v[152:155]
	v_mfma_f32_16x16x4_f32 v[156:159], v241, v21, v[156:159]
	v_mfma_f32_16x16x4_f32 v[160:163], v241, v22, v[160:163]
	v_mfma_f32_16x16x4_f32 v[164:167], v241, v23, v[164:167]
	v_mfma_f32_16x16x4_f32 v[152:155], v242, v24, v[152:155]
	v_mfma_f32_16x16x4_f32 v[156:159], v242, v25, v[156:159]
	v_mfma_f32_16x16x4_f32 v[160:163], v242, v26, v[160:163]
	v_mfma_f32_16x16x4_f32 v[164:167], v242, v27, v[164:167]
	v_mfma_f32_16x16x4_f32 v[152:155], v243, v224, v[152:155]
	v_mfma_f32_16x16x4_f32 v[156:159], v243, v225, v[156:159]
	v_mfma_f32_16x16x4_f32 v[160:163], v243, v226, v[160:163]
	v_mfma_f32_16x16x4_f32 v[164:167], v243, v227, v[164:167]
	v_mfma_f32_16x16x4_f32 v[168:171], v244, v16, 0
	v_mfma_f32_16x16x4_f32 v[172:175], v244, v17, 0
	v_mfma_f32_16x16x4_f32 v[176:179], v244, v18, 0
	v_mfma_f32_16x16x4_f32 v[180:183], v244, v19, 0
	v_mfma_f32_16x16x4_f32 v[168:171], v245, v20, v[168:171]
	v_mfma_f32_16x16x4_f32 v[172:175], v245, v21, v[172:175]
	v_mfma_f32_16x16x4_f32 v[176:179], v245, v22, v[176:179]
	v_mfma_f32_16x16x4_f32 v[180:183], v245, v23, v[180:183]
	v_mfma_f32_16x16x4_f32 v[168:171], v246, v24, v[168:171]
	v_mfma_f32_16x16x4_f32 v[172:175], v246, v25, v[172:175]
	v_mfma_f32_16x16x4_f32 v[176:179], v246, v26, v[176:179]
	v_mfma_f32_16x16x4_f32 v[180:183], v246, v27, v[180:183]
	v_mfma_f32_16x16x4_f32 v[168:171], v247, v224, v[168:171]
	v_mfma_f32_16x16x4_f32 v[172:175], v247, v225, v[172:175]
	v_mfma_f32_16x16x4_f32 v[176:179], v247, v226, v[176:179]
	v_mfma_f32_16x16x4_f32 v[180:183], v247, v227, v[180:183]
	s_nop 15
	v_add_f32_e32 v120, v228, v120
	v_add_f32_e32 v121, v228, v121
	v_add_f32_e32 v122, v228, v122
	v_add_f32_e32 v123, v228, v123
	v_mul_f32_e64 v232, |v120|, s22
	v_mul_f32_e64 v233, |v121|, s22
	v_mul_f32_e64 v234, |v122|, s22
	v_mul_f32_e64 v235, |v123|, s22
	v_exp_f32_e32 v232, v232
	v_exp_f32_e32 v233, v233
; #define LAS __attribute__((address_space(3)))
; __device__ __forceinline__ float fast_logsigmoid(float a) {
;     const float e = __builtin_amdgcn_exp2f(-1.4426950408889634f * __builtin_fabsf(a));
;     return fminf(a, 0.f) - 0.6931471805599453f * __builtin_amdgcn_logf(1.f + e);
; }
; __device__ __forceinline__ void phase_gla_kdec(Frame& F) {
;     ...
;             for (int s = 0; s < CH; ++s) { float a = bgc;
; #pragma unroll
;                 for (int r4 = 0; r4 < 4; ++r4) { const f32x4 gv = *(const LAS f32x4*)(glr + s * 16 + r4 * 4); a += (gv.x * w2c[4 * r4] + gv.y * w2c[4 * r4 + 1]) + (gv.z * w2c[4 * r4 + 2] + gv.w * w2c[4 * r4 + 3]); }
;                 run += fast_logsigmoid(a) * (1.f / 16.f); gc[s] = run; }
	v_exp_f32_e32 v234, v234
	v_exp_f32_e32 v235, v235
	v_add_f32_e32 v232, 1.0, v232
	v_add_f32_e32 v233, 1.0, v233
	v_add_f32_e32 v234, 1.0, v234
	v_add_f32_e32 v235, 1.0, v235
	v_log_f32_e32 v232, v232
	v_log_f32_e32 v233, v233
	v_log_f32_e32 v234, v234
	v_log_f32_e32 v235, v235
	v_min_f32_e32 v120, 0, v120
	v_min_f32_e32 v121, 0, v121
	v_min_f32_e32 v122, 0, v122
	v_min_f32_e32 v123, 0, v123
	v_fmac_f32_e32 v120, 0xbf317218, v232
	v_fmac_f32_e32 v121, 0xbf317218, v233
	v_fmac_f32_e32 v122, 0xbf317218, v234
	v_fmac_f32_e32 v123, 0xbf317218, v235
	v_mul_f32_e32 v120, s23, v120
	v_mul_f32_e32 v121, s23, v121
	v_mul_f32_e32 v122, s23, v122
	v_mul_f32_e32 v123, s23, v123
	v_add_f32_e32 v124, v229, v124
	v_add_f32_e32 v125, v229, v125
	v_add_f32_e32 v126, v229, v126
	v_add_f32_e32 v127, v229, v127
	v_mul_f32_e64 v232, |v124|, s22
	v_mul_f32_e64 v233, |v125|, s22
	v_mul_f32_e64 v234, |v126|, s22
	v_mul_f32_e64 v235, |v127|, s22
	v_exp_f32_e32 v232, v232
	v_exp_f32_e32 v233, v233
	v_exp_f32_e32 v234, v234
	v_exp_f32_e32 v235, v235
	v_add_f32_e32 v232, 1.0, v232
	v_add_f32_e32 v233, 1.0, v233
	v_add_f32_e32 v234, 1.0, v234
	v_add_f32_e32 v235, 1.0, v235
	v_log_f32_e32 v232, v232
	v_log_f32_e32 v233, v233
	v_log_f32_e32 v234, v234
	v_log_f32_e32 v235, v235
	v_min_f32_e32 v124, 0, v124
	v_min_f32_e32 v125, 0, v125
	v_min_f32_e32 v126, 0, v126
	v_min_f32_e32 v127, 0, v127
	v_fmac_f32_e32 v124, 0xbf317218, v232
	v_fmac_f32_e32 v125, 0xbf317218, v233
	v_fmac_f32_e32 v126, 0xbf317218, v234
	v_fmac_f32_e32 v127, 0xbf317218, v235
	v_mul_f32_e32 v124, s23, v124
	v_mul_f32_e32 v125, s23, v125
	v_mul_f32_e32 v126, s23, v126
	v_mul_f32_e32 v127, s23, v127
	v_add_f32_e32 v128, v230, v128
	v_add_f32_e32 v129, v230, v129
	v_add_f32_e32 v130, v230, v130
	v_add_f32_e32 v131, v230, v131
	v_mul_f32_e64 v232, |v128|, s22
	v_mul_f32_e64 v233, |v129|, s22
	v_mul_f32_e64 v234, |v130|, s22
	v_mul_f32_e64 v235, |v131|, s22
	v_exp_f32_e32 v232, v232
	v_exp_f32_e32 v233, v233
	v_exp_f32_e32 v234, v234
	v_exp_f32_e32 v235, v235
	v_add_f32_e32 v232, 1.0, v232
	v_add_f32_e32 v233, 1.0, v233
	v_add_f32_e32 v234, 1.0, v234
	v_add_f32_e32 v235, 1.0, v235
	v_log_f32_e32 v232, v232
	v_log_f32_e32 v233, v233
	v_log_f32_e32 v234, v234
	v_log_f32_e32 v235, v235
	v_min_f32_e32 v128, 0, v128
	v_min_f32_e32 v129, 0, v129
	v_min_f32_e32 v130, 0, v130
	v_min_f32_e32 v131, 0, v131
	v_fmac_f32_e32 v128, 0xbf317218, v232
	v_fmac_f32_e32 v129, 0xbf317218, v233
	v_fmac_f32_e32 v130, 0xbf317218, v234
	v_fmac_f32_e32 v131, 0xbf317218, v235
	v_mul_f32_e32 v128, s23, v128
	v_mul_f32_e32 v129, s23, v129
	v_mul_f32_e32 v130, s23, v130
	v_mul_f32_e32 v131, s23, v131
	v_add_f32_e32 v132, v231, v132
	v_add_f32_e32 v133, v231, v133
	v_add_f32_e32 v134, v231, v134
	v_add_f32_e32 v135, v231, v135
	v_mul_f32_e64 v232, |v132|, s22
	v_mul_f32_e64 v233, |v133|, s22
	v_mul_f32_e64 v234, |v134|, s22
	v_mul_f32_e64 v235, |v135|, s22
	v_exp_f32_e32 v232, v232
	v_exp_f32_e32 v233, v233
	v_exp_f32_e32 v234, v234
	v_exp_f32_e32 v235, v235
	v_add_f32_e32 v232, 1.0, v232
	v_add_f32_e32 v233, 1.0, v233
	v_add_f32_e32 v234, 1.0, v234
	v_add_f32_e32 v235, 1.0, v235
	v_log_f32_e32 v232, v232
	v_log_f32_e32 v233, v233
	v_log_f32_e32 v234, v234
	v_log_f32_e32 v235, v235
	v_min_f32_e32 v132, 0, v132
	v_min_f32_e32 v133, 0, v133
	v_min_f32_e32 v134, 0, v134
	v_min_f32_e32 v135, 0, v135
	v_fmac_f32_e32 v132, 0xbf317218, v232
	v_fmac_f32_e32 v133, 0xbf317218, v233
	v_fmac_f32_e32 v134, 0xbf317218, v234
	v_fmac_f32_e32 v135, 0xbf317218, v235
	v_mul_f32_e32 v132, s23, v132
	v_mul_f32_e32 v133, s23, v133
	v_mul_f32_e32 v134, s23, v134
	v_mul_f32_e32 v135, s23, v135
	v_add_f32_e32 v136, v228, v136
	v_add_f32_e32 v137, v228, v137
	v_add_f32_e32 v138, v228, v138
	v_add_f32_e32 v139, v228, v139
	v_mul_f32_e64 v232, |v136|, s22
	v_mul_f32_e64 v233, |v137|, s22
	v_mul_f32_e64 v234, |v138|, s22
	v_mul_f32_e64 v235, |v139|, s22
	v_exp_f32_e32 v232, v232
	v_exp_f32_e32 v233, v233
	v_exp_f32_e32 v234, v234
	v_exp_f32_e32 v235, v235
	v_add_f32_e32 v232, 1.0, v232
	v_add_f32_e32 v233, 1.0, v233
	v_add_f32_e32 v234, 1.0, v234
	v_add_f32_e32 v235, 1.0, v235
	v_log_f32_e32 v232, v232
	v_log_f32_e32 v233, v233
	v_log_f32_e32 v234, v234
	v_log_f32_e32 v235, v235
	v_min_f32_e32 v136, 0, v136
	v_min_f32_e32 v137, 0, v137
	v_min_f32_e32 v138, 0, v138
	v_min_f32_e32 v139, 0, v139
	v_fmac_f32_e32 v136, 0xbf317218, v232
	v_fmac_f32_e32 v137, 0xbf317218, v233
	v_fmac_f32_e32 v138, 0xbf317218, v234
	v_fmac_f32_e32 v139, 0xbf317218, v235
	v_mul_f32_e32 v136, s23, v136
	v_mul_f32_e32 v137, s23, v137
	v_mul_f32_e32 v138, s23, v138
	v_mul_f32_e32 v139, s23, v139
	v_add_f32_e32 v140, v229, v140
	v_add_f32_e32 v141, v229, v141
	v_add_f32_e32 v142, v229, v142
	v_add_f32_e32 v143, v229, v143
	v_mul_f32_e64 v232, |v140|, s22
	v_mul_f32_e64 v233, |v141|, s22
	v_mul_f32_e64 v234, |v142|, s22
	v_mul_f32_e64 v235, |v143|, s22
	v_exp_f32_e32 v232, v232
	v_exp_f32_e32 v233, v233
	v_exp_f32_e32 v234, v234
	v_exp_f32_e32 v235, v235
	v_add_f32_e32 v232, 1.0, v232
	v_add_f32_e32 v233, 1.0, v233
	v_add_f32_e32 v234, 1.0, v234
	v_add_f32_e32 v235, 1.0, v235
	v_log_f32_e32 v232, v232
	v_log_f32_e32 v233, v233
	v_log_f32_e32 v234, v234
	v_log_f32_e32 v235, v235
	v_min_f32_e32 v140, 0, v140
	v_min_f32_e32 v141, 0, v141
	v_min_f32_e32 v142, 0, v142
	v_min_f32_e32 v143, 0, v143
	v_fmac_f32_e32 v140, 0xbf317218, v232
	v_fmac_f32_e32 v141, 0xbf317218, v233
	v_fmac_f32_e32 v142, 0xbf317218, v234
	v_fmac_f32_e32 v143, 0xbf317218, v235
	v_mul_f32_e32 v140, s23, v140
	v_mul_f32_e32 v141, s23, v141
	v_mul_f32_e32 v142, s23, v142
	v_mul_f32_e32 v143, s23, v143
	v_add_f32_e32 v144, v230, v144
; #define LAS __attribute__((address_space(3)))
; __device__ __forceinline__ float fast_logsigmoid(float a) {
;     const float e = __builtin_amdgcn_exp2f(-1.4426950408889634f * __builtin_fabsf(a));
;     return fminf(a, 0.f) - 0.6931471805599453f * __builtin_amdgcn_logf(1.f + e);
; }
; __device__ __forceinline__ void phase_gla_kdec(Frame& F) {
;     ...
;             for (int s = 0; s < CH; ++s) { float a = bgc;
; #pragma unroll
;                 for (int r4 = 0; r4 < 4; ++r4) { const f32x4 gv = *(const LAS f32x4*)(glr + s * 16 + r4 * 4); a += (gv.x * w2c[4 * r4] + gv.y * w2c[4 * r4 + 1]) + (gv.z * w2c[4 * r4 + 2] + gv.w * w2c[4 * r4 + 3]); }
;                 run += fast_logsigmoid(a) * (1.f / 16.f); gc[s] = run; }
	v_add_f32_e32 v145, v230, v145
	v_add_f32_e32 v146, v230, v146
	v_add_f32_e32 v147, v230, v147
	v_mul_f32_e64 v232, |v144|, s22
	v_mul_f32_e64 v233, |v145|, s22
	v_mul_f32_e64 v234, |v146|, s22
	v_mul_f32_e64 v235, |v147|, s22
	v_exp_f32_e32 v232, v232
	v_exp_f32_e32 v233, v233
	v_exp_f32_e32 v234, v234
	v_exp_f32_e32 v235, v235
	v_add_f32_e32 v232, 1.0, v232
	v_add_f32_e32 v233, 1.0, v233
	v_add_f32_e32 v234, 1.0, v234
	v_add_f32_e32 v235, 1.0, v235
	v_log_f32_e32 v232, v232
	v_log_f32_e32 v233, v233
	v_log_f32_e32 v234, v234
	v_log_f32_e32 v235, v235
	v_min_f32_e32 v144, 0, v144
	v_min_f32_e32 v145, 0, v145
	v_min_f32_e32 v146, 0, v146
	v_min_f32_e32 v147, 0, v147
	v_fmac_f32_e32 v144, 0xbf317218, v232
	v_fmac_f32_e32 v145, 0xbf317218, v233
	v_fmac_f32_e32 v146, 0xbf317218, v234
	v_fmac_f32_e32 v147, 0xbf317218, v235
	v_mul_f32_e32 v144, s23, v144
	v_mul_f32_e32 v145, s23, v145
	v_mul_f32_e32 v146, s23, v146
	v_mul_f32_e32 v147, s23, v147
	v_add_f32_e32 v148, v231, v148
	v_add_f32_e32 v149, v231, v149
	v_add_f32_e32 v150, v231, v150
	v_add_f32_e32 v151, v231, v151
	v_mul_f32_e64 v232, |v148|, s22
	v_mul_f32_e64 v233, |v149|, s22
	v_mul_f32_e64 v234, |v150|, s22
	v_mul_f32_e64 v235, |v151|, s22
	v_exp_f32_e32 v232, v232
	v_exp_f32_e32 v233, v233
	v_exp_f32_e32 v234, v234
	v_exp_f32_e32 v235, v235
	v_add_f32_e32 v232, 1.0, v232
	v_add_f32_e32 v233, 1.0, v233
	v_add_f32_e32 v234, 1.0, v234
	v_add_f32_e32 v235, 1.0, v235
	v_log_f32_e32 v232, v232
	v_log_f32_e32 v233, v233
	v_log_f32_e32 v234, v234
	v_log_f32_e32 v235, v235
	v_min_f32_e32 v148, 0, v148
	v_min_f32_e32 v149, 0, v149
	v_min_f32_e32 v150, 0, v150
	v_min_f32_e32 v151, 0, v151
	v_fmac_f32_e32 v148, 0xbf317218, v232
	v_fmac_f32_e32 v149, 0xbf317218, v233
	v_fmac_f32_e32 v150, 0xbf317218, v234
	v_fmac_f32_e32 v151, 0xbf317218, v235
	v_mul_f32_e32 v148, s23, v148
	v_mul_f32_e32 v149, s23, v149
	v_mul_f32_e32 v150, s23, v150
	v_mul_f32_e32 v151, s23, v151
	v_add_f32_e32 v152, v228, v152
	v_add_f32_e32 v153, v228, v153
	v_add_f32_e32 v154, v228, v154
	v_add_f32_e32 v155, v228, v155
	v_mul_f32_e64 v232, |v152|, s22
	v_mul_f32_e64 v233, |v153|, s22
	v_mul_f32_e64 v234, |v154|, s22
	v_mul_f32_e64 v235, |v155|, s22
	v_exp_f32_e32 v232, v232
	v_exp_f32_e32 v233, v233
	v_exp_f32_e32 v234, v234
	v_exp_f32_e32 v235, v235
	v_add_f32_e32 v232, 1.0, v232
	v_add_f32_e32 v233, 1.0, v233
	v_add_f32_e32 v234, 1.0, v234
	v_add_f32_e32 v235, 1.0, v235
	v_log_f32_e32 v232, v232
	v_log_f32_e32 v233, v233
	v_log_f32_e32 v234, v234
	v_log_f32_e32 v235, v235
	v_min_f32_e32 v152, 0, v152
	v_min_f32_e32 v153, 0, v153
	v_min_f32_e32 v154, 0, v154
	v_min_f32_e32 v155, 0, v155
	v_fmac_f32_e32 v152, 0xbf317218, v232
	v_fmac_f32_e32 v153, 0xbf317218, v233
	v_fmac_f32_e32 v154, 0xbf317218, v234
	v_fmac_f32_e32 v155, 0xbf317218, v235
	v_mul_f32_e32 v152, s23, v152
	v_mul_f32_e32 v153, s23, v153
	v_mul_f32_e32 v154, s23, v154
	v_mul_f32_e32 v155, s23, v155
	v_add_f32_e32 v156, v229, v156
	v_add_f32_e32 v157, v229, v157
	v_add_f32_e32 v158, v229, v158
	v_add_f32_e32 v159, v229, v159
	v_mul_f32_e64 v232, |v156|, s22
	v_mul_f32_e64 v233, |v157|, s22
	v_mul_f32_e64 v234, |v158|, s22
	v_mul_f32_e64 v235, |v159|, s22
	v_exp_f32_e32 v232, v232
	v_exp_f32_e32 v233, v233
	v_exp_f32_e32 v234, v234
	v_exp_f32_e32 v235, v235
	v_add_f32_e32 v232, 1.0, v232
	v_add_f32_e32 v233, 1.0, v233
	v_add_f32_e32 v234, 1.0, v234
	v_add_f32_e32 v235, 1.0, v235
	v_log_f32_e32 v232, v232
	v_log_f32_e32 v233, v233
	v_log_f32_e32 v234, v234
	v_log_f32_e32 v235, v235
	v_min_f32_e32 v156, 0, v156
	v_min_f32_e32 v157, 0, v157
	v_min_f32_e32 v158, 0, v158
	v_min_f32_e32 v159, 0, v159
	v_fmac_f32_e32 v156, 0xbf317218, v232
	v_fmac_f32_e32 v157, 0xbf317218, v233
	v_fmac_f32_e32 v158, 0xbf317218, v234
	v_fmac_f32_e32 v159, 0xbf317218, v235
	v_mul_f32_e32 v156, s23, v156
	v_mul_f32_e32 v157, s23, v157
	v_mul_f32_e32 v158, s23, v158
	v_mul_f32_e32 v159, s23, v159
	v_add_f32_e32 v160, v230, v160
	v_add_f32_e32 v161, v230, v161
	v_add_f32_e32 v162, v230, v162
	v_add_f32_e32 v163, v230, v163
	v_mul_f32_e64 v232, |v160|, s22
	v_mul_f32_e64 v233, |v161|, s22
	v_mul_f32_e64 v234, |v162|, s22
	v_mul_f32_e64 v235, |v163|, s22
	v_exp_f32_e32 v232, v232
	v_exp_f32_e32 v233, v233
	v_exp_f32_e32 v234, v234
	v_exp_f32_e32 v235, v235
	v_add_f32_e32 v232, 1.0, v232
	v_add_f32_e32 v233, 1.0, v233
	v_add_f32_e32 v234, 1.0, v234
	v_add_f32_e32 v235, 1.0, v235
	v_log_f32_e32 v232, v232
	v_log_f32_e32 v233, v233
	v_log_f32_e32 v234, v234
	v_log_f32_e32 v235, v235
	v_min_f32_e32 v160, 0, v160
	v_min_f32_e32 v161, 0, v161
	v_min_f32_e32 v162, 0, v162
	v_min_f32_e32 v163, 0, v163
	v_fmac_f32_e32 v160, 0xbf317218, v232
	v_fmac_f32_e32 v161, 0xbf317218, v233
	v_fmac_f32_e32 v162, 0xbf317218, v234
	v_fmac_f32_e32 v163, 0xbf317218, v235
	v_mul_f32_e32 v160, s23, v160
	v_mul_f32_e32 v161, s23, v161
	v_mul_f32_e32 v162, s23, v162
	v_mul_f32_e32 v163, s23, v163
	v_add_f32_e32 v164, v231, v164
	v_add_f32_e32 v165, v231, v165
	v_add_f32_e32 v166, v231, v166
	v_add_f32_e32 v167, v231, v167
	v_mul_f32_e64 v232, |v164|, s22
	v_mul_f32_e64 v233, |v165|, s22
	v_mul_f32_e64 v234, |v166|, s22
	v_mul_f32_e64 v235, |v167|, s22
	v_exp_f32_e32 v232, v232
	v_exp_f32_e32 v233, v233
	v_exp_f32_e32 v234, v234
	v_exp_f32_e32 v235, v235
	v_add_f32_e32 v232, 1.0, v232
	v_add_f32_e32 v233, 1.0, v233
	v_add_f32_e32 v234, 1.0, v234
	v_add_f32_e32 v235, 1.0, v235
	v_log_f32_e32 v232, v232
	v_log_f32_e32 v233, v233
	v_log_f32_e32 v234, v234
	v_log_f32_e32 v235, v235
	v_min_f32_e32 v164, 0, v164
	v_min_f32_e32 v165, 0, v165
	v_min_f32_e32 v166, 0, v166
	v_min_f32_e32 v167, 0, v167
	v_fmac_f32_e32 v164, 0xbf317218, v232
; #define LAS __attribute__((address_space(3)))
; __device__ __forceinline__ void phase_gla_kdec(Frame& F) {
;     ...
;             for (int s = 0; s < CH; ++s) { float a = bgc;
; #pragma unroll
;                 for (int r4 = 0; r4 < 4; ++r4) { const f32x4 gv = *(const LAS f32x4*)(glr + s * 16 + r4 * 4); a += (gv.x * w2c[4 * r4] + gv.y * w2c[4 * r4 + 1]) + (gv.z * w2c[4 * r4 + 2] + gv.w * w2c[4 * r4 + 3]); }
;                 run += fast_logsigmoid(a) * (1.f / 16.f); gc[s] = run; }
	v_fmac_f32_e32 v165, 0xbf317218, v233
	v_fmac_f32_e32 v166, 0xbf317218, v234
	v_fmac_f32_e32 v167, 0xbf317218, v235
	v_mul_f32_e32 v164, s23, v164
	v_mul_f32_e32 v165, s23, v165
	v_mul_f32_e32 v166, s23, v166
	v_mul_f32_e32 v167, s23, v167
	v_add_f32_e32 v168, v228, v168
	v_add_f32_e32 v169, v228, v169
	v_add_f32_e32 v170, v228, v170
	v_add_f32_e32 v171, v228, v171
	v_mul_f32_e64 v232, |v168|, s22
	v_mul_f32_e64 v233, |v169|, s22
	v_mul_f32_e64 v234, |v170|, s22
	v_mul_f32_e64 v235, |v171|, s22
	v_exp_f32_e32 v232, v232
	v_exp_f32_e32 v233, v233
	v_exp_f32_e32 v234, v234
	v_exp_f32_e32 v235, v235
	v_add_f32_e32 v232, 1.0, v232
	v_add_f32_e32 v233, 1.0, v233
	v_add_f32_e32 v234, 1.0, v234
	v_add_f32_e32 v235, 1.0, v235
	v_log_f32_e32 v232, v232
	v_log_f32_e32 v233, v233
	v_log_f32_e32 v234, v234
	v_log_f32_e32 v235, v235
	v_min_f32_e32 v168, 0, v168
	v_min_f32_e32 v169, 0, v169
	v_min_f32_e32 v170, 0, v170
	v_min_f32_e32 v171, 0, v171
	v_fmac_f32_e32 v168, 0xbf317218, v232
	v_fmac_f32_e32 v169, 0xbf317218, v233
	v_fmac_f32_e32 v170, 0xbf317218, v234
	v_fmac_f32_e32 v171, 0xbf317218, v235
	v_mul_f32_e32 v168, s23, v168
	v_mul_f32_e32 v169, s23, v169
	v_mul_f32_e32 v170, s23, v170
	v_mul_f32_e32 v171, s23, v171
	v_add_f32_e32 v172, v229, v172
	v_add_f32_e32 v173, v229, v173
	v_add_f32_e32 v174, v229, v174
	v_add_f32_e32 v175, v229, v175
	v_mul_f32_e64 v232, |v172|, s22
	v_mul_f32_e64 v233, |v173|, s22
	v_mul_f32_e64 v234, |v174|, s22
	v_mul_f32_e64 v235, |v175|, s22
	v_exp_f32_e32 v232, v232
	v_exp_f32_e32 v233, v233
	v_exp_f32_e32 v234, v234
	v_exp_f32_e32 v235, v235
	v_add_f32_e32 v232, 1.0, v232
	v_add_f32_e32 v233, 1.0, v233
	v_add_f32_e32 v234, 1.0, v234
	v_add_f32_e32 v235, 1.0, v235
	v_log_f32_e32 v232, v232
	v_log_f32_e32 v233, v233
	v_log_f32_e32 v234, v234
	v_log_f32_e32 v235, v235
	v_min_f32_e32 v172, 0, v172
	v_min_f32_e32 v173, 0, v173
	v_min_f32_e32 v174, 0, v174
	v_min_f32_e32 v175, 0, v175
	v_fmac_f32_e32 v172, 0xbf317218, v232
	v_fmac_f32_e32 v173, 0xbf317218, v233
	v_fmac_f32_e32 v174, 0xbf317218, v234
	v_fmac_f32_e32 v175, 0xbf317218, v235
	v_mul_f32_e32 v172, s23, v172
	v_mul_f32_e32 v173, s23, v173
	v_mul_f32_e32 v174, s23, v174
	v_mul_f32_e32 v175, s23, v175
	v_add_f32_e32 v176, v230, v176
	v_add_f32_e32 v177, v230, v177
	v_add_f32_e32 v178, v230, v178
	v_add_f32_e32 v179, v230, v179
	v_mul_f32_e64 v232, |v176|, s22
	v_mul_f32_e64 v233, |v177|, s22
	v_mul_f32_e64 v234, |v178|, s22
	v_mul_f32_e64 v235, |v179|, s22
	v_exp_f32_e32 v232, v232
	v_exp_f32_e32 v233, v233
	v_exp_f32_e32 v234, v234
	v_exp_f32_e32 v235, v235
	v_add_f32_e32 v232, 1.0, v232
	v_add_f32_e32 v233, 1.0, v233
	v_add_f32_e32 v234, 1.0, v234
	v_add_f32_e32 v235, 1.0, v235
	v_log_f32_e32 v232, v232
	v_log_f32_e32 v233, v233
	v_log_f32_e32 v234, v234
	v_log_f32_e32 v235, v235
	v_min_f32_e32 v176, 0, v176
	v_min_f32_e32 v177, 0, v177
	v_min_f32_e32 v178, 0, v178
	v_min_f32_e32 v179, 0, v179
	v_fmac_f32_e32 v176, 0xbf317218, v232
	v_fmac_f32_e32 v177, 0xbf317218, v233
	v_fmac_f32_e32 v178, 0xbf317218, v234
	v_fmac_f32_e32 v179, 0xbf317218, v235
	v_mul_f32_e32 v176, s23, v176
	v_mul_f32_e32 v177, s23, v177
	v_mul_f32_e32 v178, s23, v178
	v_mul_f32_e32 v179, s23, v179
	v_add_f32_e32 v180, v231, v180
	v_add_f32_e32 v181, v231, v181
	v_add_f32_e32 v182, v231, v182
	v_add_f32_e32 v183, v231, v183
	v_mul_f32_e64 v232, |v180|, s22
	v_mul_f32_e64 v233, |v181|, s22
	v_mul_f32_e64 v234, |v182|, s22
	v_mul_f32_e64 v235, |v183|, s22
	v_exp_f32_e32 v232, v232
	v_exp_f32_e32 v233, v233
	v_exp_f32_e32 v234, v234
	v_exp_f32_e32 v235, v235
	v_add_f32_e32 v232, 1.0, v232
	v_add_f32_e32 v233, 1.0, v233
	v_add_f32_e32 v234, 1.0, v234
	v_add_f32_e32 v235, 1.0, v235
	v_log_f32_e32 v232, v232
	v_log_f32_e32 v233, v233
	v_log_f32_e32 v234, v234
	v_log_f32_e32 v235, v235
	v_min_f32_e32 v180, 0, v180
	v_min_f32_e32 v181, 0, v181
	v_min_f32_e32 v182, 0, v182
	v_min_f32_e32 v183, 0, v183
	v_fmac_f32_e32 v180, 0xbf317218, v232
	v_fmac_f32_e32 v181, 0xbf317218, v233
	v_fmac_f32_e32 v182, 0xbf317218, v234
	v_fmac_f32_e32 v183, 0xbf317218, v235
	v_mul_f32_e32 v180, s23, v180
	v_mul_f32_e32 v181, s23, v181
	v_mul_f32_e32 v182, s23, v182
	v_mul_f32_e32 v183, s23, v183
	v_add_f32_e32 v121, v120, v121
	v_add_f32_e32 v122, v121, v122
	v_add_f32_e32 v123, v122, v123
	v_add_f32_e32 v136, v123, v136
	v_add_f32_e32 v137, v136, v137
	v_add_f32_e32 v138, v137, v138
	v_add_f32_e32 v139, v138, v139
	v_add_f32_e32 v152, v139, v152
	v_add_f32_e32 v153, v152, v153
	v_add_f32_e32 v154, v153, v154
	v_add_f32_e32 v155, v154, v155
	v_add_f32_e32 v168, v155, v168
	v_add_f32_e32 v169, v168, v169
	v_add_f32_e32 v170, v169, v170
	v_add_f32_e32 v171, v170, v171
	v_add_f32_e32 v125, v124, v125
	v_add_f32_e32 v126, v125, v126
	v_add_f32_e32 v127, v126, v127
	v_add_f32_e32 v140, v127, v140
	v_add_f32_e32 v141, v140, v141
	v_add_f32_e32 v142, v141, v142
	v_add_f32_e32 v143, v142, v143
	v_add_f32_e32 v156, v143, v156
	v_add_f32_e32 v157, v156, v157
	v_add_f32_e32 v158, v157, v158
	v_add_f32_e32 v159, v158, v159
	v_add_f32_e32 v172, v159, v172
	v_add_f32_e32 v173, v172, v173
	v_add_f32_e32 v174, v173, v174
	v_add_f32_e32 v175, v174, v175
	v_add_f32_e32 v129, v128, v129
	v_add_f32_e32 v130, v129, v130
	v_add_f32_e32 v131, v130, v131
	v_add_f32_e32 v144, v131, v144
	v_add_f32_e32 v145, v144, v145
	v_add_f32_e32 v146, v145, v146
	v_add_f32_e32 v147, v146, v147
	v_add_f32_e32 v160, v147, v160
	v_add_f32_e32 v161, v160, v161
	v_add_f32_e32 v162, v161, v162
	v_add_f32_e32 v163, v162, v163
	v_add_f32_e32 v176, v163, v176
	v_add_f32_e32 v177, v176, v177
	v_add_f32_e32 v178, v177, v178
	v_add_f32_e32 v179, v178, v179
	v_add_f32_e32 v133, v132, v133
	v_add_f32_e32 v134, v133, v134
	v_add_f32_e32 v135, v134, v135
	v_add_f32_e32 v148, v135, v148
	v_add_f32_e32 v149, v148, v149
	v_add_f32_e32 v150, v149, v150
	v_add_f32_e32 v151, v150, v151
	v_add_f32_e32 v164, v151, v164
	v_add_f32_e32 v165, v164, v165
	v_add_f32_e32 v166, v165, v166
	v_add_f32_e32 v167, v166, v167
	v_add_f32_e32 v180, v167, v180
	v_add_f32_e32 v181, v180, v181
	v_add_f32_e32 v182, v181, v182
	v_add_f32_e32 v183, v182, v183
	v_mov_b32_e32 v88, v171
	v_mov_b32_e32 v89, v175
	v_mov_b32_e32 v90, v179
	v_mov_b32_e32 v91, v183
	ds_write_b128 v186, v[88:91]
	s_waitcnt lgkmcnt(0)
; __device__ __forceinline__ unsigned f2bf(float f) { unsigned u = __builtin_bit_cast(unsigned, f); return (u + 0x7fffu + ((u >> 16) & 1u)) >> 16; }
; __device__ __forceinline__ void phase_gla_kdec(Frame& F) {
;     ...
;                 run += fast_logsigmoid(a) * (1.f / 16.f); gc[s] = run; }
; #pragma unroll
;             for (int s = 0; s < CH; ++s) { const float kv = bf2f(kt[s * KP + j]);
;                 kt[s * KP + j] = (bf16_t)f2bf(kv * __builtin_amdgcn_exp2f(1.4426950408889634f * (run - gc[s]))); }
;             DEC[(size_t)unit * QKW + j] = __builtin_amdgcn_exp2f(1.4426950408889634f * run); }
	ds_read_b128 v[232:235], v187 offset:0
	ds_read_b128 v[236:239], v187 offset:256
	ds_read_b128 v[240:243], v187 offset:512
	ds_read_b128 v[244:247], v187 offset:768
	v_cmp_eq_u32_e32 vcc, 0, v119
	s_nop 1
	v_cndmask_b32_e64 v92, 0, 1.0, vcc
	v_cmp_gt_u32_e32 vcc, 2, v119
	s_nop 1
	v_cndmask_b32_e64 v93, 0, 1.0, vcc
	v_cmp_gt_u32_e32 vcc, 3, v119
	s_nop 1
	v_cndmask_b32_e64 v94, 0, 1.0, vcc
	s_waitcnt lgkmcnt(0)
	v_mov_b32_e32 v248, v244
	v_fmac_f32_e32 v248, v94, v240
	v_fmac_f32_e32 v248, v93, v236
	v_fmac_f32_e32 v248, v92, v232
	v_mov_b32_e32 v249, v245
	v_fmac_f32_e32 v249, v94, v241
	v_fmac_f32_e32 v249, v93, v237
	v_fmac_f32_e32 v249, v92, v233
	v_mov_b32_e32 v250, v246
	v_fmac_f32_e32 v250, v94, v242
	v_fmac_f32_e32 v250, v93, v238
	v_fmac_f32_e32 v250, v92, v234
	v_mov_b32_e32 v251, v247
	v_fmac_f32_e32 v251, v94, v243
	v_fmac_f32_e32 v251, v93, v239
	v_fmac_f32_e32 v251, v92, v235
	v_mul_f32_e32 v88, 0x3fb8aa3b, v248
	v_mul_f32_e32 v89, 0x3fb8aa3b, v249
	v_mul_f32_e32 v90, 0x3fb8aa3b, v250
	v_mul_f32_e32 v91, 0x3fb8aa3b, v251
	v_exp_f32_e32 v88, v88
	v_exp_f32_e32 v89, v89
	v_exp_f32_e32 v90, v90
	v_exp_f32_e32 v91, v91
	v_mul_u32_u24_e32 v232, 12, v118
	v_mov_b32_e32 v233, 0
	v_lshl_add_u64 v[232:233], v[28:29], 0, v[232:233]
	v_lshl_add_u64 v[232:233], v[232:233], 0, s[0:1]
	v_cmp_eq_u32_e32 vcc, 0, v119
	s_and_b64 exec, exec, vcc
	global_store_dwordx4 v[232:233], v[88:91], off
	s_nop 1
	s_mov_b64 exec, -1
	ds_read_b64 v[232:233], v185 offset:0
	ds_read_b64 v[234:235], v185 offset:1040
	ds_read_b64 v[236:237], v185 offset:2080
	ds_read_b64 v[238:239], v185 offset:3120
	ds_read_b64 v[240:241], v185 offset:4160
	ds_read_b64 v[242:243], v185 offset:5200
	ds_read_b64 v[244:245], v185 offset:6240
	ds_read_b64 v[246:247], v185 offset:7280
	v_sub_f32_e32 v120, v248, v120
	v_mul_f32_e32 v120, 0x3fb8aa3b, v120
	v_exp_f32_e32 v120, v120
	v_sub_f32_e32 v124, v249, v124
	v_mul_f32_e32 v124, 0x3fb8aa3b, v124
	v_exp_f32_e32 v124, v124
	v_sub_f32_e32 v128, v250, v128
	v_mul_f32_e32 v128, 0x3fb8aa3b, v128
	v_exp_f32_e32 v128, v128
	v_sub_f32_e32 v132, v251, v132
	v_mul_f32_e32 v132, 0x3fb8aa3b, v132
	v_exp_f32_e32 v132, v132
	s_waitcnt lgkmcnt(7)
	v_lshlrev_b32_e32 v92, 16, v232
	v_and_b32_e32 v93, 0xffff0000, v232
	v_lshlrev_b32_e32 v94, 16, v233
	v_and_b32_e32 v95, 0xffff0000, v233
	v_mul_f32_e32 v92, v120, v92
	v_mul_f32_e32 v93, v124, v93
	v_mul_f32_e32 v94, v128, v94
	v_mul_f32_e32 v95, v132, v95
	v_cvt_pk_bf16_f32 v88, v92, v93
	v_cvt_pk_bf16_f32 v89, v94, v95
	ds_write_b64 v185, v[88:89] offset:0
	v_sub_f32_e32 v121, v248, v121
	v_mul_f32_e32 v121, 0x3fb8aa3b, v121
	v_exp_f32_e32 v121, v121
	v_sub_f32_e32 v125, v249, v125
	v_mul_f32_e32 v125, 0x3fb8aa3b, v125
	v_exp_f32_e32 v125, v125
	v_sub_f32_e32 v129, v250, v129
	v_mul_f32_e32 v129, 0x3fb8aa3b, v129
	v_exp_f32_e32 v129, v129
	v_sub_f32_e32 v133, v251, v133
	v_mul_f32_e32 v133, 0x3fb8aa3b, v133
	v_exp_f32_e32 v133, v133
	s_waitcnt lgkmcnt(6)
	v_lshlrev_b32_e32 v92, 16, v234
	v_and_b32_e32 v93, 0xffff0000, v234
	v_lshlrev_b32_e32 v94, 16, v235
	v_and_b32_e32 v95, 0xffff0000, v235
	v_mul_f32_e32 v92, v121, v92
	v_mul_f32_e32 v93, v125, v93
	v_mul_f32_e32 v94, v129, v94
	v_mul_f32_e32 v95, v133, v95
	v_cvt_pk_bf16_f32 v90, v92, v93
	v_cvt_pk_bf16_f32 v91, v94, v95
	ds_write_b64 v185, v[90:91] offset:1040
	v_sub_f32_e32 v122, v248, v122
	v_mul_f32_e32 v122, 0x3fb8aa3b, v122
	v_exp_f32_e32 v122, v122
	v_sub_f32_e32 v126, v249, v126
	v_mul_f32_e32 v126, 0x3fb8aa3b, v126
	v_exp_f32_e32 v126, v126
	v_sub_f32_e32 v130, v250, v130
	v_mul_f32_e32 v130, 0x3fb8aa3b, v130
	v_exp_f32_e32 v130, v130
	v_sub_f32_e32 v134, v251, v134
	v_mul_f32_e32 v134, 0x3fb8aa3b, v134
	v_exp_f32_e32 v134, v134
	s_waitcnt lgkmcnt(5)
	v_lshlrev_b32_e32 v92, 16, v236
	v_and_b32_e32 v93, 0xffff0000, v236
	v_lshlrev_b32_e32 v94, 16, v237
	v_and_b32_e32 v95, 0xffff0000, v237
	v_mul_f32_e32 v92, v122, v92
	v_mul_f32_e32 v93, v126, v93
	v_mul_f32_e32 v94, v130, v94
	v_mul_f32_e32 v95, v134, v95
	v_cvt_pk_bf16_f32 v88, v92, v93
	v_cvt_pk_bf16_f32 v89, v94, v95
	ds_write_b64 v185, v[88:89] offset:2080
	v_sub_f32_e32 v123, v248, v123
	v_mul_f32_e32 v123, 0x3fb8aa3b, v123
	v_exp_f32_e32 v123, v123
	v_sub_f32_e32 v127, v249, v127
	v_mul_f32_e32 v127, 0x3fb8aa3b, v127
	v_exp_f32_e32 v127, v127
	v_sub_f32_e32 v131, v250, v131
	v_mul_f32_e32 v131, 0x3fb8aa3b, v131
	v_exp_f32_e32 v131, v131
	v_sub_f32_e32 v135, v251, v135
	v_mul_f32_e32 v135, 0x3fb8aa3b, v135
	v_exp_f32_e32 v135, v135
	s_waitcnt lgkmcnt(4)
	v_lshlrev_b32_e32 v92, 16, v238
	v_and_b32_e32 v93, 0xffff0000, v238
	v_lshlrev_b32_e32 v94, 16, v239
	v_and_b32_e32 v95, 0xffff0000, v239
	v_mul_f32_e32 v92, v123, v92
	v_mul_f32_e32 v93, v127, v93
	v_mul_f32_e32 v94, v131, v94
	v_mul_f32_e32 v95, v135, v95
	v_cvt_pk_bf16_f32 v90, v92, v93
	v_cvt_pk_bf16_f32 v91, v94, v95
	ds_write_b64 v185, v[90:91] offset:3120
	v_sub_f32_e32 v136, v248, v136
	v_mul_f32_e32 v136, 0x3fb8aa3b, v136
	v_exp_f32_e32 v136, v136
	v_sub_f32_e32 v140, v249, v140
	v_mul_f32_e32 v140, 0x3fb8aa3b, v140
	v_exp_f32_e32 v140, v140
	v_sub_f32_e32 v144, v250, v144
	v_mul_f32_e32 v144, 0x3fb8aa3b, v144
	v_exp_f32_e32 v144, v144
	v_sub_f32_e32 v148, v251, v148
	v_mul_f32_e32 v148, 0x3fb8aa3b, v148
	v_exp_f32_e32 v148, v148
	s_waitcnt lgkmcnt(3)
; __device__ __forceinline__ unsigned f2bf(float f) { unsigned u = __builtin_bit_cast(unsigned, f); return (u + 0x7fffu + ((u >> 16) & 1u)) >> 16; }
; __device__ __forceinline__ void phase_gla_kdec(Frame& F) {
;     ...
;             for (int s = 0; s < CH; ++s) { const float kv = bf2f(kt[s * KP + j]);
;                 kt[s * KP + j] = (bf16_t)f2bf(kv * __builtin_amdgcn_exp2f(1.4426950408889634f * (run - gc[s]))); }
	v_lshlrev_b32_e32 v92, 16, v240
	v_and_b32_e32 v93, 0xffff0000, v240
	v_lshlrev_b32_e32 v94, 16, v241
	v_and_b32_e32 v95, 0xffff0000, v241
	v_mul_f32_e32 v92, v136, v92
	v_mul_f32_e32 v93, v140, v93
	v_mul_f32_e32 v94, v144, v94
	v_mul_f32_e32 v95, v148, v95
	v_cvt_pk_bf16_f32 v88, v92, v93
	v_cvt_pk_bf16_f32 v89, v94, v95
	ds_write_b64 v185, v[88:89] offset:4160
	v_sub_f32_e32 v137, v248, v137
	v_mul_f32_e32 v137, 0x3fb8aa3b, v137
	v_exp_f32_e32 v137, v137
	v_sub_f32_e32 v141, v249, v141
	v_mul_f32_e32 v141, 0x3fb8aa3b, v141
	v_exp_f32_e32 v141, v141
	v_sub_f32_e32 v145, v250, v145
	v_mul_f32_e32 v145, 0x3fb8aa3b, v145
	v_exp_f32_e32 v145, v145
	v_sub_f32_e32 v149, v251, v149
	v_mul_f32_e32 v149, 0x3fb8aa3b, v149
	v_exp_f32_e32 v149, v149
	s_waitcnt lgkmcnt(2)
	v_lshlrev_b32_e32 v92, 16, v242
	v_and_b32_e32 v93, 0xffff0000, v242
	v_lshlrev_b32_e32 v94, 16, v243
	v_and_b32_e32 v95, 0xffff0000, v243
	v_mul_f32_e32 v92, v137, v92
	v_mul_f32_e32 v93, v141, v93
	v_mul_f32_e32 v94, v145, v94
	v_mul_f32_e32 v95, v149, v95
	v_cvt_pk_bf16_f32 v90, v92, v93
	v_cvt_pk_bf16_f32 v91, v94, v95
	ds_write_b64 v185, v[90:91] offset:5200
	v_sub_f32_e32 v138, v248, v138
	v_mul_f32_e32 v138, 0x3fb8aa3b, v138
	v_exp_f32_e32 v138, v138
	v_sub_f32_e32 v142, v249, v142
	v_mul_f32_e32 v142, 0x3fb8aa3b, v142
	v_exp_f32_e32 v142, v142
	v_sub_f32_e32 v146, v250, v146
	v_mul_f32_e32 v146, 0x3fb8aa3b, v146
	v_exp_f32_e32 v146, v146
	v_sub_f32_e32 v150, v251, v150
	v_mul_f32_e32 v150, 0x3fb8aa3b, v150
	v_exp_f32_e32 v150, v150
	s_waitcnt lgkmcnt(1)
	v_lshlrev_b32_e32 v92, 16, v244
	v_and_b32_e32 v93, 0xffff0000, v244
	v_lshlrev_b32_e32 v94, 16, v245
	v_and_b32_e32 v95, 0xffff0000, v245
	v_mul_f32_e32 v92, v138, v92
	v_mul_f32_e32 v93, v142, v93
	v_mul_f32_e32 v94, v146, v94
	v_mul_f32_e32 v95, v150, v95
	v_cvt_pk_bf16_f32 v88, v92, v93
	v_cvt_pk_bf16_f32 v89, v94, v95
	ds_write_b64 v185, v[88:89] offset:6240
	v_sub_f32_e32 v139, v248, v139
	v_mul_f32_e32 v139, 0x3fb8aa3b, v139
	v_exp_f32_e32 v139, v139
	v_sub_f32_e32 v143, v249, v143
	v_mul_f32_e32 v143, 0x3fb8aa3b, v143
	v_exp_f32_e32 v143, v143
	v_sub_f32_e32 v147, v250, v147
	v_mul_f32_e32 v147, 0x3fb8aa3b, v147
	v_exp_f32_e32 v147, v147
	v_sub_f32_e32 v151, v251, v151
	v_mul_f32_e32 v151, 0x3fb8aa3b, v151
	v_exp_f32_e32 v151, v151
	s_waitcnt lgkmcnt(0)
	v_lshlrev_b32_e32 v92, 16, v246
	v_and_b32_e32 v93, 0xffff0000, v246
	v_lshlrev_b32_e32 v94, 16, v247
	v_and_b32_e32 v95, 0xffff0000, v247
	v_mul_f32_e32 v92, v139, v92
	v_mul_f32_e32 v93, v143, v93
	v_mul_f32_e32 v94, v147, v94
	v_mul_f32_e32 v95, v151, v95
	v_cvt_pk_bf16_f32 v90, v92, v93
	v_cvt_pk_bf16_f32 v91, v94, v95
	ds_write_b64 v185, v[90:91] offset:7280
	ds_read_b64 v[232:233], v185 offset:8320
	ds_read_b64 v[234:235], v185 offset:9360
	ds_read_b64 v[236:237], v185 offset:10400
	ds_read_b64 v[238:239], v185 offset:11440
	ds_read_b64 v[240:241], v185 offset:12480
	ds_read_b64 v[242:243], v185 offset:13520
	ds_read_b64 v[244:245], v185 offset:14560
	ds_read_b64 v[246:247], v185 offset:15600
	v_sub_f32_e32 v152, v248, v152
	v_mul_f32_e32 v152, 0x3fb8aa3b, v152
	v_exp_f32_e32 v152, v152
	v_sub_f32_e32 v156, v249, v156
	v_mul_f32_e32 v156, 0x3fb8aa3b, v156
	v_exp_f32_e32 v156, v156
	v_sub_f32_e32 v160, v250, v160
	v_mul_f32_e32 v160, 0x3fb8aa3b, v160
	v_exp_f32_e32 v160, v160
	v_sub_f32_e32 v164, v251, v164
	v_mul_f32_e32 v164, 0x3fb8aa3b, v164
	v_exp_f32_e32 v164, v164
	s_waitcnt lgkmcnt(7)
	v_lshlrev_b32_e32 v92, 16, v232
	v_and_b32_e32 v93, 0xffff0000, v232
	v_lshlrev_b32_e32 v94, 16, v233
	v_and_b32_e32 v95, 0xffff0000, v233
	v_mul_f32_e32 v92, v152, v92
	v_mul_f32_e32 v93, v156, v93
	v_mul_f32_e32 v94, v160, v94
	v_mul_f32_e32 v95, v164, v95
	v_cvt_pk_bf16_f32 v88, v92, v93
	v_cvt_pk_bf16_f32 v89, v94, v95
	ds_write_b64 v185, v[88:89] offset:8320
	v_sub_f32_e32 v153, v248, v153
	v_mul_f32_e32 v153, 0x3fb8aa3b, v153
	v_exp_f32_e32 v153, v153
	v_sub_f32_e32 v157, v249, v157
	v_mul_f32_e32 v157, 0x3fb8aa3b, v157
	v_exp_f32_e32 v157, v157
	v_sub_f32_e32 v161, v250, v161
	v_mul_f32_e32 v161, 0x3fb8aa3b, v161
	v_exp_f32_e32 v161, v161
	v_sub_f32_e32 v165, v251, v165
	v_mul_f32_e32 v165, 0x3fb8aa3b, v165
	v_exp_f32_e32 v165, v165
	s_waitcnt lgkmcnt(6)
	v_lshlrev_b32_e32 v92, 16, v234
	v_and_b32_e32 v93, 0xffff0000, v234
	v_lshlrev_b32_e32 v94, 16, v235
	v_and_b32_e32 v95, 0xffff0000, v235
	v_mul_f32_e32 v92, v153, v92
	v_mul_f32_e32 v93, v157, v93
	v_mul_f32_e32 v94, v161, v94
	v_mul_f32_e32 v95, v165, v95
	v_cvt_pk_bf16_f32 v90, v92, v93
	v_cvt_pk_bf16_f32 v91, v94, v95
	ds_write_b64 v185, v[90:91] offset:9360
	v_sub_f32_e32 v154, v248, v154
	v_mul_f32_e32 v154, 0x3fb8aa3b, v154
	v_exp_f32_e32 v154, v154
	v_sub_f32_e32 v158, v249, v158
	v_mul_f32_e32 v158, 0x3fb8aa3b, v158
	v_exp_f32_e32 v158, v158
	v_sub_f32_e32 v162, v250, v162
	v_mul_f32_e32 v162, 0x3fb8aa3b, v162
	v_exp_f32_e32 v162, v162
	v_sub_f32_e32 v166, v251, v166
	v_mul_f32_e32 v166, 0x3fb8aa3b, v166
	v_exp_f32_e32 v166, v166
	s_waitcnt lgkmcnt(5)
; __device__ __forceinline__ unsigned f2bf(float f) { unsigned u = __builtin_bit_cast(unsigned, f); return (u + 0x7fffu + ((u >> 16) & 1u)) >> 16; }
; __device__ __forceinline__ void phase_gla_kdec(Frame& F) {
;     ...
;             for (int s = 0; s < CH; ++s) { const float kv = bf2f(kt[s * KP + j]);
;                 kt[s * KP + j] = (bf16_t)f2bf(kv * __builtin_amdgcn_exp2f(1.4426950408889634f * (run - gc[s]))); }
;             DEC[(size_t)unit * QKW + j] = __builtin_amdgcn_exp2f(1.4426950408889634f * run); }
	v_lshlrev_b32_e32 v92, 16, v236
	v_and_b32_e32 v93, 0xffff0000, v236
	v_lshlrev_b32_e32 v94, 16, v237
	v_and_b32_e32 v95, 0xffff0000, v237
	v_mul_f32_e32 v92, v154, v92
	v_mul_f32_e32 v93, v158, v93
	v_mul_f32_e32 v94, v162, v94
	v_mul_f32_e32 v95, v166, v95
	v_cvt_pk_bf16_f32 v88, v92, v93
	v_cvt_pk_bf16_f32 v89, v94, v95
	ds_write_b64 v185, v[88:89] offset:10400
	v_sub_f32_e32 v155, v248, v155
	v_mul_f32_e32 v155, 0x3fb8aa3b, v155
	v_exp_f32_e32 v155, v155
	v_sub_f32_e32 v159, v249, v159
	v_mul_f32_e32 v159, 0x3fb8aa3b, v159
	v_exp_f32_e32 v159, v159
	v_sub_f32_e32 v163, v250, v163
	v_mul_f32_e32 v163, 0x3fb8aa3b, v163
	v_exp_f32_e32 v163, v163
	v_sub_f32_e32 v167, v251, v167
	v_mul_f32_e32 v167, 0x3fb8aa3b, v167
	v_exp_f32_e32 v167, v167
	s_waitcnt lgkmcnt(4)
	v_lshlrev_b32_e32 v92, 16, v238
	v_and_b32_e32 v93, 0xffff0000, v238
	v_lshlrev_b32_e32 v94, 16, v239
	v_and_b32_e32 v95, 0xffff0000, v239
	v_mul_f32_e32 v92, v155, v92
	v_mul_f32_e32 v93, v159, v93
	v_mul_f32_e32 v94, v163, v94
	v_mul_f32_e32 v95, v167, v95
	v_cvt_pk_bf16_f32 v90, v92, v93
	v_cvt_pk_bf16_f32 v91, v94, v95
	ds_write_b64 v185, v[90:91] offset:11440
	v_sub_f32_e32 v168, v248, v168
	v_mul_f32_e32 v168, 0x3fb8aa3b, v168
	v_exp_f32_e32 v168, v168
	v_sub_f32_e32 v172, v249, v172
	v_mul_f32_e32 v172, 0x3fb8aa3b, v172
	v_exp_f32_e32 v172, v172
	v_sub_f32_e32 v176, v250, v176
	v_mul_f32_e32 v176, 0x3fb8aa3b, v176
	v_exp_f32_e32 v176, v176
	v_sub_f32_e32 v180, v251, v180
	v_mul_f32_e32 v180, 0x3fb8aa3b, v180
	v_exp_f32_e32 v180, v180
	s_waitcnt lgkmcnt(3)
	v_lshlrev_b32_e32 v92, 16, v240
	v_and_b32_e32 v93, 0xffff0000, v240
	v_lshlrev_b32_e32 v94, 16, v241
	v_and_b32_e32 v95, 0xffff0000, v241
	v_mul_f32_e32 v92, v168, v92
	v_mul_f32_e32 v93, v172, v93
	v_mul_f32_e32 v94, v176, v94
	v_mul_f32_e32 v95, v180, v95
	v_cvt_pk_bf16_f32 v88, v92, v93
	v_cvt_pk_bf16_f32 v89, v94, v95
	ds_write_b64 v185, v[88:89] offset:12480
	v_sub_f32_e32 v169, v248, v169
	v_mul_f32_e32 v169, 0x3fb8aa3b, v169
	v_exp_f32_e32 v169, v169
	v_sub_f32_e32 v173, v249, v173
	v_mul_f32_e32 v173, 0x3fb8aa3b, v173
	v_exp_f32_e32 v173, v173
	v_sub_f32_e32 v177, v250, v177
	v_mul_f32_e32 v177, 0x3fb8aa3b, v177
	v_exp_f32_e32 v177, v177
	v_sub_f32_e32 v181, v251, v181
	v_mul_f32_e32 v181, 0x3fb8aa3b, v181
	v_exp_f32_e32 v181, v181
	s_waitcnt lgkmcnt(2)
	v_lshlrev_b32_e32 v92, 16, v242
	v_and_b32_e32 v93, 0xffff0000, v242
	v_lshlrev_b32_e32 v94, 16, v243
	v_and_b32_e32 v95, 0xffff0000, v243
	v_mul_f32_e32 v92, v169, v92
	v_mul_f32_e32 v93, v173, v93
	v_mul_f32_e32 v94, v177, v94
	v_mul_f32_e32 v95, v181, v95
	v_cvt_pk_bf16_f32 v90, v92, v93
	v_cvt_pk_bf16_f32 v91, v94, v95
	ds_write_b64 v185, v[90:91] offset:13520
	v_sub_f32_e32 v170, v248, v170
	v_mul_f32_e32 v170, 0x3fb8aa3b, v170
	v_exp_f32_e32 v170, v170
	v_sub_f32_e32 v174, v249, v174
	v_mul_f32_e32 v174, 0x3fb8aa3b, v174
	v_exp_f32_e32 v174, v174
	v_sub_f32_e32 v178, v250, v178
	v_mul_f32_e32 v178, 0x3fb8aa3b, v178
	v_exp_f32_e32 v178, v178
	v_sub_f32_e32 v182, v251, v182
	v_mul_f32_e32 v182, 0x3fb8aa3b, v182
	v_exp_f32_e32 v182, v182
	s_waitcnt lgkmcnt(1)
	v_lshlrev_b32_e32 v92, 16, v244
	v_and_b32_e32 v93, 0xffff0000, v244
	v_lshlrev_b32_e32 v94, 16, v245
	v_and_b32_e32 v95, 0xffff0000, v245
	v_mul_f32_e32 v92, v170, v92
	v_mul_f32_e32 v93, v174, v93
	v_mul_f32_e32 v94, v178, v94
	v_mul_f32_e32 v95, v182, v95
	v_cvt_pk_bf16_f32 v88, v92, v93
	v_cvt_pk_bf16_f32 v89, v94, v95
	ds_write_b64 v185, v[88:89] offset:14560
	v_sub_f32_e32 v171, v248, v171
	v_mul_f32_e32 v171, 0x3fb8aa3b, v171
	v_exp_f32_e32 v171, v171
	v_sub_f32_e32 v175, v249, v175
	v_mul_f32_e32 v175, 0x3fb8aa3b, v175
	v_exp_f32_e32 v175, v175
	v_sub_f32_e32 v179, v250, v179
	v_mul_f32_e32 v179, 0x3fb8aa3b, v179
	v_exp_f32_e32 v179, v179
	v_sub_f32_e32 v183, v251, v183
	v_mul_f32_e32 v183, 0x3fb8aa3b, v183
	v_exp_f32_e32 v183, v183
	s_waitcnt lgkmcnt(0)
	v_lshlrev_b32_e32 v92, 16, v246
	v_and_b32_e32 v93, 0xffff0000, v246
	v_lshlrev_b32_e32 v94, 16, v247
	v_and_b32_e32 v95, 0xffff0000, v247
	v_mul_f32_e32 v92, v171, v92
	v_mul_f32_e32 v93, v175, v93
	v_mul_f32_e32 v94, v179, v94
	v_mul_f32_e32 v95, v183, v95
	v_cvt_pk_bf16_f32 v90, v92, v93
	v_cvt_pk_bf16_f32 v91, v94, v95
	ds_write_b64 v185, v[90:91] offset:15600
	v_mov_b64_e32 v[92:93], v[82:83]
	v_mov_b64_e32 v[88:89], v[86:87]
	v_mov_b64_e32 v[90:91], v[84:85]
	v_mov_b64_e32 v[94:95], v[80:81]
	s_mov_b32 s0, 0
	s_branch .LBB0_819
